# hyena Toeplitz conv loops software-pipelined (4-deep LDS prefetch, running base regs, immediate offsets); bit-identical accumulation order
# speedup vs baseline: 1.0234x; 1.0162x over previous
.LBB0_726:
	s_or_b64 exec, exec, s[50:51]
	v_ashrrev_i32_e32 v21, 31, v20
	v_lshl_add_u64 v[20:21], v[20:21], 2, s[26:27]
	global_load_dword v24, v[20:21], off
	s_movk_i32 s50, 0xfee0
	v_mov_b32_e32 v44, v41
	v_mov_b32_e32 v19, v18
	v_mov_b32_e32 v20, v18
	v_mov_b32_e32 v21, v18
	v_mov_b32_e32 v156, v44
	v_add_lshl_u32 v155, v35, s50, 1
	v_and_b32_e32 v155, -4, v155
	v_add_u32_e32 v155, v25, v155
	v_add_u32_e32 v154, 0x8260, v155
	ds_read_b128 v[236:239], v156
	ds_read2_b32 v[204:205], v154 offset1:1
	ds_read2_b32 v[206:207], v154 offset0:2 offset1:3
	ds_read_b32 v208, v154 offset:16
	ds_read_b128 v[240:243], v156 offset:64
	ds_read2_b32 v[210:211], v154 offset0:16 offset1:17
	ds_read2_b32 v[212:213], v154 offset0:18 offset1:19
	ds_read_b32 v214, v154 offset:80
	ds_read_b128 v[244:247], v156 offset:128
	ds_read2_b32 v[216:217], v154 offset0:32 offset1:33
	ds_read2_b32 v[218:219], v154 offset0:34 offset1:35
	ds_read_b32 v220, v154 offset:144
	ds_read_b128 v[144:147], v156 offset:192
	ds_read2_b32 v[222:223], v154 offset0:48 offset1:49
	ds_read2_b32 v[224:225], v154 offset0:50 offset1:51
	ds_read_b32 v226, v154 offset:208
	s_waitcnt lgkmcnt(12)
	v_alignbyte_b32 v228, v205, v204, v36
	v_alignbyte_b32 v229, v206, v205, v36
	v_alignbyte_b32 v230, v207, v206, v36
	v_alignbyte_b32 v231, v208, v207, v36
	ds_read2_b32 v[204:205], v154 offset0:64 offset1:65
	ds_read2_b32 v[206:207], v154 offset0:66 offset1:67
	ds_read_b32 v208, v154 offset:272
	v_mfma_f32_16x16x32_bf16 v[18:21], v[228:231], v[236:239], v[18:21]
	ds_read_b128 v[236:239], v156 offset:256
	s_waitcnt lgkmcnt(12)
	v_alignbyte_b32 v232, v211, v210, v36
	v_alignbyte_b32 v233, v212, v211, v36
	v_alignbyte_b32 v234, v213, v212, v36
	v_alignbyte_b32 v235, v214, v213, v36
	ds_read2_b32 v[210:211], v154 offset0:80 offset1:81
	ds_read2_b32 v[212:213], v154 offset0:82 offset1:83
	ds_read_b32 v214, v154 offset:336
	v_mfma_f32_16x16x32_bf16 v[18:21], v[232:235], v[240:243], v[18:21]
	ds_read_b128 v[240:243], v156 offset:320
	s_waitcnt lgkmcnt(12)
	v_alignbyte_b32 v228, v217, v216, v36
	v_alignbyte_b32 v229, v218, v217, v36
	v_alignbyte_b32 v230, v219, v218, v36
	v_alignbyte_b32 v231, v220, v219, v36
	ds_read2_b32 v[216:217], v154 offset0:96 offset1:97
	ds_read2_b32 v[218:219], v154 offset0:98 offset1:99
	ds_read_b32 v220, v154 offset:400
	v_mfma_f32_16x16x32_bf16 v[18:21], v[228:231], v[244:247], v[18:21]
	ds_read_b128 v[244:247], v156 offset:384
	s_waitcnt lgkmcnt(12)
	v_alignbyte_b32 v232, v223, v222, v36
	v_alignbyte_b32 v233, v224, v223, v36
	v_alignbyte_b32 v234, v225, v224, v36
	v_alignbyte_b32 v235, v226, v225, v36
	ds_read2_b32 v[222:223], v154 offset0:112 offset1:113
	ds_read2_b32 v[224:225], v154 offset0:114 offset1:115
	ds_read_b32 v226, v154 offset:464
	v_mfma_f32_16x16x32_bf16 v[18:21], v[232:235], v[144:147], v[18:21]
	ds_read_b128 v[144:147], v156 offset:448
	s_waitcnt lgkmcnt(12)
	v_alignbyte_b32 v228, v205, v204, v36
	v_alignbyte_b32 v229, v206, v205, v36
	v_alignbyte_b32 v230, v207, v206, v36
	v_alignbyte_b32 v231, v208, v207, v36
	ds_read2_b32 v[204:205], v154 offset0:128 offset1:129
	ds_read2_b32 v[206:207], v154 offset0:130 offset1:131
	ds_read_b32 v208, v154 offset:528
	v_mfma_f32_16x16x32_bf16 v[18:21], v[228:231], v[236:239], v[18:21]
	ds_read_b128 v[236:239], v156 offset:512
	s_waitcnt lgkmcnt(12)
	v_alignbyte_b32 v232, v211, v210, v36
	v_alignbyte_b32 v233, v212, v211, v36
	v_alignbyte_b32 v234, v213, v212, v36
	v_alignbyte_b32 v235, v214, v213, v36
	ds_read2_b32 v[210:211], v154 offset0:144 offset1:145
	ds_read2_b32 v[212:213], v154 offset0:146 offset1:147
	ds_read_b32 v214, v154 offset:592
	v_mfma_f32_16x16x32_bf16 v[18:21], v[232:235], v[240:243], v[18:21]
	ds_read_b128 v[240:243], v156 offset:576
	s_waitcnt lgkmcnt(12)
	v_alignbyte_b32 v228, v217, v216, v36
	v_alignbyte_b32 v229, v218, v217, v36
	v_alignbyte_b32 v230, v219, v218, v36
	v_alignbyte_b32 v231, v220, v219, v36
	ds_read2_b32 v[216:217], v154 offset0:160 offset1:161
	ds_read2_b32 v[218:219], v154 offset0:162 offset1:163
	ds_read_b32 v220, v154 offset:656
	v_mfma_f32_16x16x32_bf16 v[18:21], v[228:231], v[244:247], v[18:21]
	ds_read_b128 v[244:247], v156 offset:640
	s_waitcnt lgkmcnt(12)
	v_alignbyte_b32 v232, v223, v222, v36
	v_alignbyte_b32 v233, v224, v223, v36
	v_alignbyte_b32 v234, v225, v224, v36
	v_alignbyte_b32 v235, v226, v225, v36
	ds_read2_b32 v[222:223], v154 offset0:176 offset1:177
	ds_read2_b32 v[224:225], v154 offset0:178 offset1:179
	ds_read_b32 v226, v154 offset:720
	v_mfma_f32_16x16x32_bf16 v[18:21], v[232:235], v[144:147], v[18:21]
	ds_read_b128 v[144:147], v156 offset:704
	s_waitcnt lgkmcnt(12)
	v_alignbyte_b32 v228, v205, v204, v36
	v_alignbyte_b32 v229, v206, v205, v36
	v_alignbyte_b32 v230, v207, v206, v36
	v_alignbyte_b32 v231, v208, v207, v36
	ds_read2_b32 v[204:205], v154 offset0:192 offset1:193
	ds_read2_b32 v[206:207], v154 offset0:194 offset1:195
	ds_read_b32 v208, v154 offset:784
	v_mfma_f32_16x16x32_bf16 v[18:21], v[228:231], v[236:239], v[18:21]
	ds_read_b128 v[236:239], v156 offset:768
	s_waitcnt lgkmcnt(12)
	v_alignbyte_b32 v232, v211, v210, v36
	v_alignbyte_b32 v233, v212, v211, v36
	v_alignbyte_b32 v234, v213, v212, v36
	v_alignbyte_b32 v235, v214, v213, v36
	ds_read2_b32 v[210:211], v154 offset0:208 offset1:209
	ds_read2_b32 v[212:213], v154 offset0:210 offset1:211
	ds_read_b32 v214, v154 offset:848
	v_mfma_f32_16x16x32_bf16 v[18:21], v[232:235], v[240:243], v[18:21]
	ds_read_b128 v[240:243], v156 offset:832
	s_waitcnt lgkmcnt(12)
	v_alignbyte_b32 v228, v217, v216, v36
	v_alignbyte_b32 v229, v218, v217, v36
	v_alignbyte_b32 v230, v219, v218, v36
	v_alignbyte_b32 v231, v220, v219, v36
	ds_read2_b32 v[216:217], v154 offset0:224 offset1:225
	ds_read2_b32 v[218:219], v154 offset0:226 offset1:227
	ds_read_b32 v220, v154 offset:912
	v_mfma_f32_16x16x32_bf16 v[18:21], v[228:231], v[244:247], v[18:21]
	ds_read_b128 v[244:247], v156 offset:896
	s_waitcnt lgkmcnt(12)
	v_alignbyte_b32 v232, v223, v222, v36
	v_alignbyte_b32 v233, v224, v223, v36
	v_alignbyte_b32 v234, v225, v224, v36
	v_alignbyte_b32 v235, v226, v225, v36
	ds_read2_b32 v[222:223], v154 offset0:240 offset1:241
	ds_read2_b32 v[224:225], v154 offset0:242 offset1:243
	ds_read_b32 v226, v154 offset:976
	v_mfma_f32_16x16x32_bf16 v[18:21], v[232:235], v[144:147], v[18:21]
	ds_read_b128 v[144:147], v156 offset:960
	s_waitcnt lgkmcnt(12)
	v_alignbyte_b32 v228, v205, v204, v36
	v_alignbyte_b32 v229, v206, v205, v36
	v_alignbyte_b32 v230, v207, v206, v36
	v_alignbyte_b32 v231, v208, v207, v36
	s_nop 1
	v_mfma_f32_16x16x32_bf16 v[18:21], v[228:231], v[236:239], v[18:21]
	s_waitcnt lgkmcnt(8)
	v_alignbyte_b32 v232, v211, v210, v36
	v_alignbyte_b32 v233, v212, v211, v36
	v_alignbyte_b32 v234, v213, v212, v36
	v_alignbyte_b32 v235, v214, v213, v36
	s_nop 1
	v_mfma_f32_16x16x32_bf16 v[18:21], v[232:235], v[240:243], v[18:21]
	s_waitcnt lgkmcnt(4)
	v_alignbyte_b32 v228, v217, v216, v36
	v_alignbyte_b32 v229, v218, v217, v36
	v_alignbyte_b32 v230, v219, v218, v36
	v_alignbyte_b32 v231, v220, v219, v36
	s_nop 1
	v_mfma_f32_16x16x32_bf16 v[18:21], v[228:231], v[244:247], v[18:21]
	s_waitcnt lgkmcnt(0)
	v_alignbyte_b32 v232, v223, v222, v36
	v_alignbyte_b32 v233, v224, v223, v36
	v_alignbyte_b32 v234, v225, v224, v36
	v_alignbyte_b32 v235, v226, v225, v36
	s_nop 1
	v_mfma_f32_16x16x32_bf16 v[18:21], v[232:235], v[144:147], v[18:21]
	v_add_u32_e32 v45, s53, v1
	s_movk_i32 s50, 0x600
	v_add_f32_e32 v42, v42, v43
	v_mul_lo_u32 v46, v45, s50
	v_div_scale_f32 v43, s[50:51], v42, v42, 1.0
	v_rcp_f32_e32 v44, v43
	s_nop 0
	v_fma_f32 v47, -v43, v44, 1.0
	v_fmac_f32_e32 v44, v47, v44
	v_div_scale_f32 v47, vcc, 1.0, v42, 1.0
	v_mul_f32_e32 v48, v47, v44
	v_fma_f32 v49, -v43, v48, v47
	v_fmac_f32_e32 v48, v49, v44
	v_fma_f32 v43, -v43, v48, v47
	v_div_fmas_f32 v43, v43, v44, v48
	v_div_fixup_f32 v44, v43, v42, 1.0
	v_lshlrev_b32_e32 v42, 1, v37
	v_add3_u32 v42, s17, v46, v42
	ds_read_b64 v[46:47], v42 offset:512
	v_lshl_add_u32 v43, v45, 9, v38
	ds_read_b64 v[48:49], v43 offset:24576
	s_waitcnt lgkmcnt(1)
	v_and_b32_e32 v53, 0xffff0000, v46
	v_lshlrev_b32_e32 v52, 16, v46
	v_pk_mul_f32 v[52:53], v[110:111], v[52:53] op_sel_hi:[0,1]
	s_waitcnt lgkmcnt(0)
	v_and_b32_e32 v51, 0xffff0000, v48
	v_lshlrev_b32_e32 v50, 16, v48
	v_pk_fma_f32 v[18:19], v[44:45], v[18:19], v[52:53] op_sel_hi:[0,1,1]
	v_pk_mul_f32 v[18:19], v[18:19], v[50:51]
	v_and_b32_e32 v51, 0xffff0000, v49
	v_lshlrev_b32_e32 v50, 16, v49
	v_and_b32_e32 v49, 0xffff0000, v47
	v_lshlrev_b32_e32 v48, 16, v47
	v_pk_mul_f32 v[46:47], v[110:111], v[48:49] op_sel_hi:[0,1]
	v_pk_fma_f32 v[20:21], v[44:45], v[20:21], v[46:47] op_sel_hi:[0,1,1]
	v_pk_mul_f32 v[20:21], v[20:21], v[50:51]
	v_bfe_u32 v45, v19, 16, 1
	v_bfe_u32 v43, v21, 16, 1
	v_bfe_u32 v44, v20, 16, 1
	v_bfe_u32 v46, v18, 16, 1
	v_add3_u32 v18, v18, v46, s94
	v_add3_u32 v45, v19, v45, s94
	v_add3_u32 v19, v20, v44, s94
	v_add3_u32 v20, v21, v43, s94
	v_perm_b32 v19, v20, v19, s95
	v_perm_b32 v18, v45, v18, s95
	ds_write_b64 v42, v[18:19] offset:512
	s_waitcnt vmcnt(1)
	ds_write_b128 v28, v[14:17] offset:32800
	s_and_saveexec_b64 s[50:51], s[44:45]
	ds_write_b128 v28, v[10:13] offset:33824
	s_or_b64 exec, exec, s[50:51]
	ds_bpermute_b32 v14, v29, v27
	s_or_b32 s50, s52, 1
	s_cmp_gt_u32 s50, 6
	s_waitcnt lgkmcnt(0)
	v_add_f32_e32 v14, v27, v14
	ds_bpermute_b32 v15, v30, v14
	s_waitcnt lgkmcnt(0)
	v_add_f32_e32 v14, v14, v15
	ds_bpermute_b32 v15, v31, v14
	s_waitcnt lgkmcnt(0)
	v_add_f32_e32 v14, v14, v15
	ds_bpermute_b32 v15, v32, v14
	s_waitcnt lgkmcnt(0)
	v_add_f32_e32 v14, v14, v15
	ds_bpermute_b32 v15, v33, v14
	s_waitcnt lgkmcnt(0)
	v_add_f32_e32 v18, v14, v15
	ds_bpermute_b32 v19, v34, v18
	s_cbranch_scc1 .LBB0_736
	v_add_u32_e32 v16, 4, v26
	v_add_u32_e32 v2, s74, v16
	v_mad_i64_i32 v[14:15], s[50:51], v2, s9, v[22:23]
	global_load_dwordx4 v[2:5], v[14:15], off
	s_and_saveexec_b64 s[50:51], s[44:45]
	s_cbranch_execz .LBB0_733
	global_load_dwordx4 v[6:9], v[14:15], off offset:1024

.LBB0_736:
	v_mov_b32_e32 v14, 0
	s_mov_b32 s50, 0
	s_movk_i32 s51, 0xfee0
	v_mov_b32_e32 v15, v14
	v_mov_b32_e32 v16, v14
	v_mov_b32_e32 v17, v14
	v_mov_b32_e32 v156, v41
	v_add_lshl_u32 v155, v35, s51, 1
	v_and_b32_e32 v155, -4, v155
	v_add_u32_e32 v155, v25, v155
	v_add_u32_e32 v154, 0x8260, v155
	ds_read_b128 v[236:239], v156
	ds_read2_b32 v[204:205], v154 offset1:1
	ds_read2_b32 v[206:207], v154 offset0:2 offset1:3
	ds_read_b32 v208, v154 offset:16
	ds_read_b128 v[240:243], v156 offset:64
	ds_read2_b32 v[210:211], v154 offset0:16 offset1:17
	ds_read2_b32 v[212:213], v154 offset0:18 offset1:19
	ds_read_b32 v214, v154 offset:80
	ds_read_b128 v[244:247], v156 offset:128
	ds_read2_b32 v[216:217], v154 offset0:32 offset1:33
	ds_read2_b32 v[218:219], v154 offset0:34 offset1:35
	ds_read_b32 v220, v154 offset:144
	ds_read_b128 v[144:147], v156 offset:192
	ds_read2_b32 v[222:223], v154 offset0:48 offset1:49
	ds_read2_b32 v[224:225], v154 offset0:50 offset1:51
	ds_read_b32 v226, v154 offset:208
	s_waitcnt lgkmcnt(12)
	v_alignbyte_b32 v228, v205, v204, v36
	v_alignbyte_b32 v229, v206, v205, v36
	v_alignbyte_b32 v230, v207, v206, v36
	v_alignbyte_b32 v231, v208, v207, v36
	ds_read2_b32 v[204:205], v154 offset0:64 offset1:65
	ds_read2_b32 v[206:207], v154 offset0:66 offset1:67
	ds_read_b32 v208, v154 offset:272
	v_mfma_f32_16x16x32_bf16 v[14:17], v[228:231], v[236:239], v[14:17]
	ds_read_b128 v[236:239], v156 offset:256
	s_waitcnt lgkmcnt(12)
	v_alignbyte_b32 v232, v211, v210, v36
	v_alignbyte_b32 v233, v212, v211, v36
	v_alignbyte_b32 v234, v213, v212, v36
	v_alignbyte_b32 v235, v214, v213, v36
	ds_read2_b32 v[210:211], v154 offset0:80 offset1:81
	ds_read2_b32 v[212:213], v154 offset0:82 offset1:83
	ds_read_b32 v214, v154 offset:336
	v_mfma_f32_16x16x32_bf16 v[14:17], v[232:235], v[240:243], v[14:17]
	ds_read_b128 v[240:243], v156 offset:320
	s_waitcnt lgkmcnt(12)
	v_alignbyte_b32 v228, v217, v216, v36
	v_alignbyte_b32 v229, v218, v217, v36
	v_alignbyte_b32 v230, v219, v218, v36
	v_alignbyte_b32 v231, v220, v219, v36
	ds_read2_b32 v[216:217], v154 offset0:96 offset1:97
	ds_read2_b32 v[218:219], v154 offset0:98 offset1:99
	ds_read_b32 v220, v154 offset:400
	v_mfma_f32_16x16x32_bf16 v[14:17], v[228:231], v[244:247], v[14:17]
	ds_read_b128 v[244:247], v156 offset:384
	s_waitcnt lgkmcnt(12)
	v_alignbyte_b32 v232, v223, v222, v36
	v_alignbyte_b32 v233, v224, v223, v36
	v_alignbyte_b32 v234, v225, v224, v36
	v_alignbyte_b32 v235, v226, v225, v36
	ds_read2_b32 v[222:223], v154 offset0:112 offset1:113
	ds_read2_b32 v[224:225], v154 offset0:114 offset1:115
	ds_read_b32 v226, v154 offset:464
	v_mfma_f32_16x16x32_bf16 v[14:17], v[232:235], v[144:147], v[14:17]
	ds_read_b128 v[144:147], v156 offset:448
	s_waitcnt lgkmcnt(12)
	v_alignbyte_b32 v228, v205, v204, v36
	v_alignbyte_b32 v229, v206, v205, v36
	v_alignbyte_b32 v230, v207, v206, v36
	v_alignbyte_b32 v231, v208, v207, v36
	ds_read2_b32 v[204:205], v154 offset0:128 offset1:129
	ds_read2_b32 v[206:207], v154 offset0:130 offset1:131
	ds_read_b32 v208, v154 offset:528
	v_mfma_f32_16x16x32_bf16 v[14:17], v[228:231], v[236:239], v[14:17]
	ds_read_b128 v[236:239], v156 offset:512
	s_waitcnt lgkmcnt(12)
	v_alignbyte_b32 v232, v211, v210, v36
	v_alignbyte_b32 v233, v212, v211, v36
	v_alignbyte_b32 v234, v213, v212, v36
	v_alignbyte_b32 v235, v214, v213, v36
	ds_read2_b32 v[210:211], v154 offset0:144 offset1:145
	ds_read2_b32 v[212:213], v154 offset0:146 offset1:147
	ds_read_b32 v214, v154 offset:592
	v_mfma_f32_16x16x32_bf16 v[14:17], v[232:235], v[240:243], v[14:17]
	ds_read_b128 v[240:243], v156 offset:576
	s_waitcnt lgkmcnt(12)
	v_alignbyte_b32 v228, v217, v216, v36
	v_alignbyte_b32 v229, v218, v217, v36
	v_alignbyte_b32 v230, v219, v218, v36
	v_alignbyte_b32 v231, v220, v219, v36
	ds_read2_b32 v[216:217], v154 offset0:160 offset1:161
	ds_read2_b32 v[218:219], v154 offset0:162 offset1:163
	ds_read_b32 v220, v154 offset:656
	v_mfma_f32_16x16x32_bf16 v[14:17], v[228:231], v[244:247], v[14:17]
	ds_read_b128 v[244:247], v156 offset:640
	s_waitcnt lgkmcnt(12)
	v_alignbyte_b32 v232, v223, v222, v36
	v_alignbyte_b32 v233, v224, v223, v36
	v_alignbyte_b32 v234, v225, v224, v36
	v_alignbyte_b32 v235, v226, v225, v36
	ds_read2_b32 v[222:223], v154 offset0:176 offset1:177
	ds_read2_b32 v[224:225], v154 offset0:178 offset1:179
	ds_read_b32 v226, v154 offset:720
	v_mfma_f32_16x16x32_bf16 v[14:17], v[232:235], v[144:147], v[14:17]
	ds_read_b128 v[144:147], v156 offset:704
	s_waitcnt lgkmcnt(12)
	v_alignbyte_b32 v228, v205, v204, v36
	v_alignbyte_b32 v229, v206, v205, v36
	v_alignbyte_b32 v230, v207, v206, v36
	v_alignbyte_b32 v231, v208, v207, v36
	ds_read2_b32 v[204:205], v154 offset0:192 offset1:193
	ds_read2_b32 v[206:207], v154 offset0:194 offset1:195
	ds_read_b32 v208, v154 offset:784
	v_mfma_f32_16x16x32_bf16 v[14:17], v[228:231], v[236:239], v[14:17]
	ds_read_b128 v[236:239], v156 offset:768
	s_waitcnt lgkmcnt(12)
	v_alignbyte_b32 v232, v211, v210, v36
	v_alignbyte_b32 v233, v212, v211, v36
	v_alignbyte_b32 v234, v213, v212, v36
	v_alignbyte_b32 v235, v214, v213, v36
	ds_read2_b32 v[210:211], v154 offset0:208 offset1:209
	ds_read2_b32 v[212:213], v154 offset0:210 offset1:211
	ds_read_b32 v214, v154 offset:848
	v_mfma_f32_16x16x32_bf16 v[14:17], v[232:235], v[240:243], v[14:17]
	ds_read_b128 v[240:243], v156 offset:832
	s_waitcnt lgkmcnt(12)
	v_alignbyte_b32 v228, v217, v216, v36
	v_alignbyte_b32 v229, v218, v217, v36
	v_alignbyte_b32 v230, v219, v218, v36
	v_alignbyte_b32 v231, v220, v219, v36
	ds_read2_b32 v[216:217], v154 offset0:224 offset1:225
	ds_read2_b32 v[218:219], v154 offset0:226 offset1:227
	ds_read_b32 v220, v154 offset:912
	v_mfma_f32_16x16x32_bf16 v[14:17], v[228:231], v[244:247], v[14:17]
	ds_read_b128 v[244:247], v156 offset:896
	s_waitcnt lgkmcnt(12)
	v_alignbyte_b32 v232, v223, v222, v36
	v_alignbyte_b32 v233, v224, v223, v36
	v_alignbyte_b32 v234, v225, v224, v36
	v_alignbyte_b32 v235, v226, v225, v36
	ds_read2_b32 v[222:223], v154 offset0:240 offset1:241
	ds_read2_b32 v[224:225], v154 offset0:242 offset1:243
	ds_read_b32 v226, v154 offset:976
	v_mfma_f32_16x16x32_bf16 v[14:17], v[232:235], v[144:147], v[14:17]
	ds_read_b128 v[144:147], v156 offset:960
	s_waitcnt lgkmcnt(12)
	v_alignbyte_b32 v228, v205, v204, v36
	v_alignbyte_b32 v229, v206, v205, v36
	v_alignbyte_b32 v230, v207, v206, v36
	v_alignbyte_b32 v231, v208, v207, v36
	s_nop 1
	v_mfma_f32_16x16x32_bf16 v[14:17], v[228:231], v[236:239], v[14:17]
	s_waitcnt lgkmcnt(8)
	v_alignbyte_b32 v232, v211, v210, v36
	v_alignbyte_b32 v233, v212, v211, v36
	v_alignbyte_b32 v234, v213, v212, v36
	v_alignbyte_b32 v235, v214, v213, v36
	s_nop 1
	v_mfma_f32_16x16x32_bf16 v[14:17], v[232:235], v[240:243], v[14:17]
	s_waitcnt lgkmcnt(4)
	v_alignbyte_b32 v228, v217, v216, v36
	v_alignbyte_b32 v229, v218, v217, v36
	v_alignbyte_b32 v230, v219, v218, v36
	v_alignbyte_b32 v231, v220, v219, v36
	s_nop 1
	v_mfma_f32_16x16x32_bf16 v[14:17], v[228:231], v[244:247], v[14:17]
	s_waitcnt lgkmcnt(0)
	v_alignbyte_b32 v232, v223, v222, v36
	v_alignbyte_b32 v233, v224, v223, v36
	v_alignbyte_b32 v234, v225, v224, v36
	v_alignbyte_b32 v235, v226, v225, v36
	s_nop 1
	v_mfma_f32_16x16x32_bf16 v[14:17], v[232:235], v[144:147], v[14:17]
	v_add_f32_e32 v18, v18, v19
	v_div_scale_f32 v19, s[50:51], v18, v18, 1.0
	v_rcp_f32_e32 v20, v19
	s_add_i32 s50, s52, 2
	v_add_u32_e32 v41, 0x1800, v41
	s_cmp_gt_u32 s52, 5
	v_fma_f32 v21, -v19, v20, 1.0
	v_fmac_f32_e32 v20, v21, v20
	v_div_scale_f32 v21, vcc, 1.0, v18, 1.0
	v_mul_f32_e32 v26, v21, v20
	v_fma_f32 v27, -v19, v26, v21
	v_fmac_f32_e32 v26, v27, v20
	v_fma_f32 v19, -v19, v26, v21
	v_div_fmas_f32 v19, v19, v20, v26
	ds_read_b64 v[20:21], v42 offset:512
	v_div_fixup_f32 v18, v19, v18, 1.0
	s_mov_b32 s52, s50
	s_waitcnt lgkmcnt(0)
	v_and_b32_e32 v27, 0xffff0000, v20
	v_lshlrev_b32_e32 v26, 16, v20
	s_waitcnt vmcnt(0)
	v_pk_mul_f32 v[26:27], v[24:25], v[26:27] op_sel_hi:[0,1]
	v_pk_fma_f32 v[14:15], v[18:19], v[14:15], v[26:27] op_sel_hi:[0,1,1]
	v_and_b32_e32 v27, 0xffff0000, v21
	v_lshlrev_b32_e32 v26, 16, v21
	v_pk_mul_f32 v[20:21], v[24:25], v[26:27] op_sel_hi:[0,1]
	v_pk_fma_f32 v[16:17], v[18:19], v[16:17], v[20:21] op_sel_hi:[0,1,1]
	v_bfe_u32 v18, v17, 16, 1
	v_bfe_u32 v19, v16, 16, 1
	v_bfe_u32 v20, v15, 16, 1
	v_bfe_u32 v21, v14, 16, 1
	v_add3_u32 v14, v14, v21, s94
	v_add3_u32 v20, v15, v20, s94
	v_add3_u32 v15, v16, v19, s94
	v_add3_u32 v16, v17, v18, s94
	v_perm_b32 v15, v16, v15, s95
	v_perm_b32 v14, v20, v14, s95
	ds_write_b64 v42, v[14:15] offset:512
	s_cbranch_scc0 .LBB0_720
	v_cmp_eq_u32_e32 vcc, 0, v0
	s_and_saveexec_b64 s[42:43], vcc
	s_cbranch_execz .LBB0_749
	s_lshr_b32 s22, s22, 2
	s_and_b32 s22, s22, 4
	v_readlane_b32 s44, v251, 49
	s_add_u32 s22, s44, s22
	v_readlane_b32 s44, v251, 50
	s_addc_u32 s45, s44, 0
	s_lshl_b32 s23, s23, 3
	s_add_u32 s44, s22, s23
	s_addc_u32 s45, s45, 0
	s_mov_b32 s22, 0x400001
	s_branch .LBB0_742

.LBB0_793:
	s_or_b64 exec, exec, s[88:89]
	v_add_u32_e32 v42, v77, v66
	v_ashrrev_i32_e32 v43, 31, v42
	v_lshl_add_u64 v[42:43], v[42:43], 2, s[34:35]
	v_ashrrev_i32_e32 v67, 31, v66
	global_load_dword v86, v[42:43], off
	v_lshl_add_u64 v[42:43], v[66:67], 0, s[74:75]
	v_lshl_add_u64 v[68:69], v[42:43], 2, s[26:27]
	global_load_dword v64, v[68:69], off offset:2048
	v_add_u32_e32 v89, s22, v1
	s_movk_i32 s22, 0xc00
	v_mul_lo_u32 v67, v89, s22
	v_add_u32_e32 v90, s17, v67
	v_lshlrev_b32_e32 v42, 1, v79
	v_lshlrev_b32_e32 v43, 1, v78
	v_mov_b32_e32 v46, 0
	s_xor_b64 s[88:89], s[90:91], -1
	s_xor_b64 s[90:91], s[92:93], -1
	v_add3_u32 v91, v90, v42, v43
	s_movk_i32 s22, 0xfee0
	v_mov_b32_e32 v47, v46
	v_mov_b32_e32 v48, v46
	v_mov_b32_e32 v49, v46
	v_mov_b32_e32 v42, v46
	v_mov_b32_e32 v43, v46
	v_mov_b32_e32 v44, v46
	v_mov_b32_e32 v45, v46
	v_mov_b32_e32 v54, v46
	v_mov_b32_e32 v55, v46
	v_mov_b32_e32 v56, v46
	v_mov_b32_e32 v57, v46
	v_mov_b32_e32 v50, v46
	v_mov_b32_e32 v51, v46
	v_mov_b32_e32 v52, v46
	v_mov_b32_e32 v53, v46
	v_add_lshl_u32 v158, v84, s22, 1
	v_and_b32_e32 v158, -4, v158
	v_add_u32_e32 v158, v65, v158
	v_add_u32_e32 v158, 0xa000, v158
	v_add_u32_e32 v154, 0x260, v158
	v_add_u32_e32 v155, 0x460, v158
	v_add_u32_e32 v156, 0x660, v158
	v_add_u32_e32 v157, 0x860, v158
	ds_read_b128 v[236:239], v91
	ds_read2_b32 v[204:205], v157 offset1:1
	ds_read2_b32 v[206:207], v157 offset0:2 offset1:3
	ds_read_b32 v208, v157 offset:16
	ds_read2_b32 v[210:211], v156 offset1:1
	ds_read2_b32 v[212:213], v156 offset0:2 offset1:3
	ds_read_b32 v214, v156 offset:16
	ds_read2_b32 v[216:217], v155 offset1:1
	ds_read2_b32 v[218:219], v155 offset0:2 offset1:3
	ds_read_b32 v220, v155 offset:16
	ds_read2_b32 v[222:223], v154 offset1:1
	ds_read2_b32 v[224:225], v154 offset0:2 offset1:3
	ds_read_b32 v226, v154 offset:16
.Lhl_conv_a:
	s_waitcnt lgkmcnt(9)
	v_alignbyte_b32 v228, v205, v204, v80
	v_alignbyte_b32 v229, v206, v205, v80
	v_alignbyte_b32 v230, v207, v206, v80
	v_alignbyte_b32 v231, v208, v207, v80
	ds_read2_b32 v[204:205], v157 offset0:16 offset1:17
	ds_read2_b32 v[206:207], v157 offset0:18 offset1:19
	ds_read_b32 v208, v157 offset:80
	ds_read_b128 v[240:243], v91 offset:64
	v_mfma_f32_16x16x32_bf16 v[50:53], v[228:231], v[236:239], v[50:53]
	s_waitcnt lgkmcnt(10)
	v_alignbyte_b32 v232, v211, v210, v80
	v_alignbyte_b32 v233, v212, v211, v80
	v_alignbyte_b32 v234, v213, v212, v80
	v_alignbyte_b32 v235, v214, v213, v80
	ds_read2_b32 v[210:211], v156 offset0:16 offset1:17
	ds_read2_b32 v[212:213], v156 offset0:18 offset1:19
	ds_read_b32 v214, v156 offset:80
	v_mfma_f32_16x16x32_bf16 v[54:57], v[232:235], v[236:239], v[54:57]
	s_waitcnt lgkmcnt(10)
	v_alignbyte_b32 v228, v217, v216, v80
	v_alignbyte_b32 v229, v218, v217, v80
	v_alignbyte_b32 v230, v219, v218, v80
	v_alignbyte_b32 v231, v220, v219, v80
	ds_read2_b32 v[216:217], v155 offset0:16 offset1:17
	ds_read2_b32 v[218:219], v155 offset0:18 offset1:19
	ds_read_b32 v220, v155 offset:80
	v_mfma_f32_16x16x32_bf16 v[42:45], v[228:231], v[236:239], v[42:45]
	s_waitcnt lgkmcnt(10)
	v_alignbyte_b32 v232, v223, v222, v80
	v_alignbyte_b32 v233, v224, v223, v80
	v_alignbyte_b32 v234, v225, v224, v80
	v_alignbyte_b32 v235, v226, v225, v80
	ds_read2_b32 v[222:223], v154 offset0:16 offset1:17
	ds_read2_b32 v[224:225], v154 offset0:18 offset1:19
	ds_read_b32 v226, v154 offset:80
	v_mfma_f32_16x16x32_bf16 v[46:49], v[232:235], v[236:239], v[46:49]
	s_waitcnt lgkmcnt(9)
	v_alignbyte_b32 v228, v205, v204, v80
	v_alignbyte_b32 v229, v206, v205, v80
	v_alignbyte_b32 v230, v207, v206, v80
	v_alignbyte_b32 v231, v208, v207, v80
	ds_read2_b32 v[204:205], v157 offset0:32 offset1:33
	ds_read2_b32 v[206:207], v157 offset0:34 offset1:35
	ds_read_b32 v208, v157 offset:144
	ds_read_b128 v[236:239], v91 offset:128
	v_mfma_f32_16x16x32_bf16 v[50:53], v[228:231], v[240:243], v[50:53]
	s_waitcnt lgkmcnt(10)
	v_alignbyte_b32 v232, v211, v210, v80
	v_alignbyte_b32 v233, v212, v211, v80
	v_alignbyte_b32 v234, v213, v212, v80
	v_alignbyte_b32 v235, v214, v213, v80
	ds_read2_b32 v[210:211], v156 offset0:32 offset1:33
	ds_read2_b32 v[212:213], v156 offset0:34 offset1:35
	ds_read_b32 v214, v156 offset:144
	v_mfma_f32_16x16x32_bf16 v[54:57], v[232:235], v[240:243], v[54:57]
	s_waitcnt lgkmcnt(10)
	v_alignbyte_b32 v228, v217, v216, v80
	v_alignbyte_b32 v229, v218, v217, v80
	v_alignbyte_b32 v230, v219, v218, v80
	v_alignbyte_b32 v231, v220, v219, v80
	ds_read2_b32 v[216:217], v155 offset0:32 offset1:33
	ds_read2_b32 v[218:219], v155 offset0:34 offset1:35
	ds_read_b32 v220, v155 offset:144
	v_mfma_f32_16x16x32_bf16 v[42:45], v[228:231], v[240:243], v[42:45]
	s_waitcnt lgkmcnt(10)
	v_alignbyte_b32 v232, v223, v222, v80
	v_alignbyte_b32 v233, v224, v223, v80
	v_alignbyte_b32 v234, v225, v224, v80
	v_alignbyte_b32 v235, v226, v225, v80
	ds_read2_b32 v[222:223], v154 offset0:32 offset1:33
	ds_read2_b32 v[224:225], v154 offset0:34 offset1:35
	ds_read_b32 v226, v154 offset:144
	v_add_u32_e32 v91, 0x80, v91
	v_add_u32_e32 v154, 0x80, v154
	v_add_u32_e32 v155, 0x80, v155
	v_add_u32_e32 v156, 0x80, v156
	v_add_u32_e32 v157, 0x80, v157
	s_add_i32 s22, s22, 64
	s_cmpk_gt_i32 s22, 0x3c0
	v_mfma_f32_16x16x32_bf16 v[46:49], v[232:235], v[240:243], v[46:49]
	s_cbranch_scc0 .Lhl_conv_a
	s_waitcnt lgkmcnt(0)
	v_add_f32_e32 v58, v87, v88
	v_div_scale_f32 v59, s[22:23], v58, v58, 1.0
	v_rcp_f32_e32 v60, v59
	s_nop 0
	v_fma_f32 v61, -v59, v60, 1.0
	v_fmac_f32_e32 v60, v61, v60
	v_div_scale_f32 v61, vcc, 1.0, v58, 1.0
	v_mul_f32_e32 v87, v61, v60
	v_fma_f32 v88, -v59, v87, v61
	v_fmac_f32_e32 v87, v88, v60
	v_fma_f32 v59, -v59, v87, v61
	v_div_fmas_f32 v59, v59, v60, v87
	v_div_fixup_f32 v58, v59, v58, 1.0
	v_lshl_add_u32 v59, v81, 1, v90
	ds_read2st64_b64 v[90:93], v59 offset0:1 offset1:2
	v_lshl_add_u32 v87, v89, 11, v82
	ds_read_b64 v[60:61], v87 offset:24576
	s_waitcnt lgkmcnt(1)
	v_and_b32_e32 v127, 0xffff0000, v90
	v_lshlrev_b32_e32 v126, 16, v90
	v_pk_mul_f32 v[126:127], v[100:101], v[126:127] op_sel_hi:[0,1]
	s_waitcnt lgkmcnt(0)
	v_and_b32_e32 v89, 0xffff0000, v60
	v_lshlrev_b32_e32 v88, 16, v60
	v_pk_fma_f32 v[50:51], v[58:59], v[50:51], v[126:127] op_sel_hi:[0,1,1]
	v_pk_mul_f32 v[50:51], v[50:51], v[88:89]
	v_and_b32_e32 v89, 0xffff0000, v61
	v_lshlrev_b32_e32 v88, 16, v61
	v_and_b32_e32 v61, 0xffff0000, v91
	v_lshlrev_b32_e32 v60, 16, v91
	v_pk_mul_f32 v[60:61], v[100:101], v[60:61] op_sel_hi:[0,1]
	v_pk_fma_f32 v[52:53], v[58:59], v[52:53], v[60:61] op_sel_hi:[0,1,1]
	v_pk_mul_f32 v[52:53], v[52:53], v[88:89]
	v_bfe_u32 v88, v51, 16, 1
	v_bfe_u32 v60, v53, 16, 1
	v_bfe_u32 v61, v52, 16, 1
	v_bfe_u32 v89, v50, 16, 1
	v_add3_u32 v50, v50, v89, s94
	v_add3_u32 v88, v51, v88, s94
	v_add3_u32 v51, v52, v61, s94
	v_add3_u32 v52, v53, v60, s94
	v_perm_b32 v51, v52, v51, s95
	v_perm_b32 v50, v88, v50, s95
	ds_write_b64 v59, v[50:51] offset:512
	ds_read_b64 v[50:51], v87 offset:25088
	v_and_b32_e32 v61, 0xffff0000, v92
	v_lshlrev_b32_e32 v60, 16, v92
	v_pk_mul_f32 v[60:61], v[100:101], v[60:61] op_sel_hi:[0,1]
	v_pk_fma_f32 v[54:55], v[58:59], v[54:55], v[60:61] op_sel_hi:[0,1,1]
	s_waitcnt lgkmcnt(0)
	v_and_b32_e32 v53, 0xffff0000, v50
	v_lshlrev_b32_e32 v52, 16, v50
	v_pk_mul_f32 v[52:53], v[54:55], v[52:53]
	v_and_b32_e32 v55, 0xffff0000, v51
	v_lshlrev_b32_e32 v54, 16, v51
	v_and_b32_e32 v51, 0xffff0000, v93
	v_lshlrev_b32_e32 v50, 16, v93
	v_pk_mul_f32 v[50:51], v[100:101], v[50:51] op_sel_hi:[0,1]
	v_pk_fma_f32 v[50:51], v[58:59], v[56:57], v[50:51] op_sel_hi:[0,1,1]
	v_pk_mul_f32 v[50:51], v[50:51], v[54:55]
	v_bfe_u32 v56, v53, 16, 1
	v_bfe_u32 v54, v51, 16, 1
	v_bfe_u32 v55, v50, 16, 1
	v_bfe_u32 v57, v52, 16, 1
	v_add3_u32 v52, v52, v57, s94
	v_add3_u32 v53, v53, v56, s94
	v_add3_u32 v50, v50, v55, s94
	v_add3_u32 v51, v51, v54, s94
	v_perm_b32 v51, v51, v50, s95
	v_perm_b32 v50, v53, v52, s95
	ds_write_b64 v59, v[50:51] offset:1024
	ds_read2st64_b64 v[50:53], v59 offset0:3 offset1:4
	ds_read_b64 v[54:55], v87 offset:25600
	s_waitcnt lgkmcnt(1)
	v_and_b32_e32 v61, 0xffff0000, v50
	v_lshlrev_b32_e32 v60, 16, v50
	v_pk_mul_f32 v[60:61], v[100:101], v[60:61] op_sel_hi:[0,1]
	s_waitcnt lgkmcnt(0)
	v_and_b32_e32 v57, 0xffff0000, v54
	v_lshlrev_b32_e32 v56, 16, v54
	v_pk_fma_f32 v[42:43], v[58:59], v[42:43], v[60:61] op_sel_hi:[0,1,1]
	v_pk_mul_f32 v[42:43], v[42:43], v[56:57]
	v_and_b32_e32 v57, 0xffff0000, v55
	v_lshlrev_b32_e32 v56, 16, v55
	v_and_b32_e32 v55, 0xffff0000, v51
	v_lshlrev_b32_e32 v54, 16, v51
	v_pk_mul_f32 v[50:51], v[100:101], v[54:55] op_sel_hi:[0,1]
	v_pk_fma_f32 v[44:45], v[58:59], v[44:45], v[50:51] op_sel_hi:[0,1,1]
	v_pk_mul_f32 v[44:45], v[44:45], v[56:57]
	v_bfe_u32 v54, v43, 16, 1
	v_bfe_u32 v50, v45, 16, 1
	v_bfe_u32 v51, v44, 16, 1
	v_bfe_u32 v55, v42, 16, 1
	v_add3_u32 v42, v42, v55, s94
	v_add3_u32 v54, v43, v54, s94
	v_add3_u32 v43, v44, v51, s94
	v_add3_u32 v44, v45, v50, s94
	v_perm_b32 v43, v44, v43, s95
	v_perm_b32 v42, v54, v42, s95
	ds_write_b64 v59, v[42:43] offset:1536
	ds_read_b64 v[42:43], v87 offset:26112
	v_and_b32_e32 v51, 0xffff0000, v52
	v_lshlrev_b32_e32 v50, 16, v52
	v_pk_mul_f32 v[50:51], v[100:101], v[50:51] op_sel_hi:[0,1]
	v_pk_fma_f32 v[46:47], v[58:59], v[46:47], v[50:51] op_sel_hi:[0,1,1]
	s_waitcnt lgkmcnt(0)
	v_and_b32_e32 v45, 0xffff0000, v42
	v_lshlrev_b32_e32 v44, 16, v42
	v_pk_mul_f32 v[44:45], v[46:47], v[44:45]
	v_and_b32_e32 v47, 0xffff0000, v43
	v_lshlrev_b32_e32 v46, 16, v43
	v_and_b32_e32 v43, 0xffff0000, v53
	v_lshlrev_b32_e32 v42, 16, v53
	v_pk_mul_f32 v[42:43], v[100:101], v[42:43] op_sel_hi:[0,1]
	v_pk_fma_f32 v[42:43], v[58:59], v[48:49], v[42:43] op_sel_hi:[0,1,1]
	v_pk_mul_f32 v[42:43], v[42:43], v[46:47]
	v_bfe_u32 v48, v45, 16, 1
	v_bfe_u32 v46, v43, 16, 1
	v_bfe_u32 v47, v42, 16, 1
	v_bfe_u32 v49, v44, 16, 1
	v_add3_u32 v44, v44, v49, s94
	v_add3_u32 v45, v45, v48, s94
	v_add3_u32 v42, v42, v47, s94
	v_add3_u32 v43, v43, v46, s94
	v_perm_b32 v43, v43, v42, s95
	v_perm_b32 v42, v45, v44, s95
	ds_write_b64 v59, v[42:43] offset:2048
	s_waitcnt vmcnt(5)
	ds_write_b128 v70, v[26:29] offset:40992
	s_waitcnt vmcnt(4)
	ds_write_b128 v70, v[30:33] offset:42016
	s_waitcnt vmcnt(3)
	ds_write_b128 v70, v[34:37] offset:43040
	s_waitcnt vmcnt(2)
	ds_write_b128 v70, v[38:41] offset:44064
	s_and_saveexec_b64 s[92:93], s[42:43]
	ds_write_b128 v70, v[22:25] offset:45088
	s_or_b64 exec, exec, s[92:93]
	s_waitcnt vmcnt(1)
	ds_bpermute_b32 v26, v71, v86
	s_andn2_b64 vcc, exec, s[90:91]
	s_waitcnt lgkmcnt(0)
	v_add_f32_e32 v26, v86, v26
	ds_bpermute_b32 v27, v72, v26
	s_waitcnt lgkmcnt(0)
	v_add_f32_e32 v26, v26, v27
	ds_bpermute_b32 v27, v73, v26
	s_waitcnt lgkmcnt(0)
	v_add_f32_e32 v26, v26, v27
	ds_bpermute_b32 v27, v74, v26
	s_waitcnt lgkmcnt(0)
	v_add_f32_e32 v26, v26, v27
	ds_bpermute_b32 v27, v75, v26
	s_waitcnt lgkmcnt(0)
	v_add_f32_e32 v46, v26, v27
	ds_bpermute_b32 v47, v76, v46
	s_cbranch_vccnz .LBB0_801
	v_add_u32_e32 v28, 4, v66
	v_add_u32_e32 v2, s74, v28
	v_mad_i64_i32 v[26:27], s[22:23], v2, s10, v[62:63]
	global_load_dwordx4 v[2:5], v[26:27], off
	global_load_dwordx4 v[6:9], v[26:27], off offset:1024
	global_load_dwordx4 v[10:13], v[26:27], off offset:2048
	global_load_dwordx4 v[14:17], v[26:27], off offset:3072
	s_and_saveexec_b64 s[90:91], s[42:43]
	s_cbranch_execz .LBB0_800
	v_add_co_u32_e32 v18, vcc, 0x1000, v26
	s_nop 1
	v_addc_co_u32_e32 v19, vcc, 0, v27, vcc
	global_load_dwordx4 v[18:21], v[18:19], off

.LBB0_801:
	v_mov_b32_e32 v30, 0
	v_add_u32_e32 v48, v85, v67
	s_movk_i32 s22, 0xfee0
	v_mov_b32_e32 v31, v30
	v_mov_b32_e32 v32, v30
	v_mov_b32_e32 v33, v30
	v_mov_b32_e32 v26, v30
	v_mov_b32_e32 v27, v30
	v_mov_b32_e32 v28, v30
	v_mov_b32_e32 v29, v30
	v_mov_b32_e32 v38, v30
	v_mov_b32_e32 v39, v30
	v_mov_b32_e32 v40, v30
	v_mov_b32_e32 v41, v30
	v_mov_b32_e32 v34, v30
	v_mov_b32_e32 v35, v30
	v_mov_b32_e32 v36, v30
	v_mov_b32_e32 v37, v30
	v_add_lshl_u32 v158, v84, s22, 1
	v_and_b32_e32 v158, -4, v158
	v_add_u32_e32 v158, v65, v158
	v_add_u32_e32 v158, 0xa000, v158
	v_add_u32_e32 v154, 0x260, v158
	v_add_u32_e32 v155, 0x460, v158
	v_add_u32_e32 v156, 0x660, v158
	v_add_u32_e32 v157, 0x860, v158
	ds_read_b128 v[236:239], v48
	ds_read2_b32 v[204:205], v157 offset1:1
	ds_read2_b32 v[206:207], v157 offset0:2 offset1:3
	ds_read_b32 v208, v157 offset:16
	ds_read2_b32 v[210:211], v156 offset1:1
	ds_read2_b32 v[212:213], v156 offset0:2 offset1:3
	ds_read_b32 v214, v156 offset:16
	ds_read2_b32 v[216:217], v155 offset1:1
	ds_read2_b32 v[218:219], v155 offset0:2 offset1:3
	ds_read_b32 v220, v155 offset:16
	ds_read2_b32 v[222:223], v154 offset1:1
	ds_read2_b32 v[224:225], v154 offset0:2 offset1:3
	ds_read_b32 v226, v154 offset:16
.Lhl_conv_b:
	s_waitcnt lgkmcnt(9)
	v_alignbyte_b32 v228, v205, v204, v80
	v_alignbyte_b32 v229, v206, v205, v80
	v_alignbyte_b32 v230, v207, v206, v80
	v_alignbyte_b32 v231, v208, v207, v80
	ds_read2_b32 v[204:205], v157 offset0:16 offset1:17
	ds_read2_b32 v[206:207], v157 offset0:18 offset1:19
	ds_read_b32 v208, v157 offset:80
	ds_read_b128 v[240:243], v48 offset:64
	v_mfma_f32_16x16x32_bf16 v[34:37], v[228:231], v[236:239], v[34:37]
	s_waitcnt lgkmcnt(10)
	v_alignbyte_b32 v232, v211, v210, v80
	v_alignbyte_b32 v233, v212, v211, v80
	v_alignbyte_b32 v234, v213, v212, v80
	v_alignbyte_b32 v235, v214, v213, v80
	ds_read2_b32 v[210:211], v156 offset0:16 offset1:17
	ds_read2_b32 v[212:213], v156 offset0:18 offset1:19
	ds_read_b32 v214, v156 offset:80
	v_mfma_f32_16x16x32_bf16 v[38:41], v[232:235], v[236:239], v[38:41]
	s_waitcnt lgkmcnt(10)
	v_alignbyte_b32 v228, v217, v216, v80
	v_alignbyte_b32 v229, v218, v217, v80
	v_alignbyte_b32 v230, v219, v218, v80
	v_alignbyte_b32 v231, v220, v219, v80
	ds_read2_b32 v[216:217], v155 offset0:16 offset1:17
	ds_read2_b32 v[218:219], v155 offset0:18 offset1:19
	ds_read_b32 v220, v155 offset:80
	v_mfma_f32_16x16x32_bf16 v[26:29], v[228:231], v[236:239], v[26:29]
	s_waitcnt lgkmcnt(10)
	v_alignbyte_b32 v232, v223, v222, v80
	v_alignbyte_b32 v233, v224, v223, v80
	v_alignbyte_b32 v234, v225, v224, v80
	v_alignbyte_b32 v235, v226, v225, v80
	ds_read2_b32 v[222:223], v154 offset0:16 offset1:17
	ds_read2_b32 v[224:225], v154 offset0:18 offset1:19
	ds_read_b32 v226, v154 offset:80
	v_mfma_f32_16x16x32_bf16 v[30:33], v[232:235], v[236:239], v[30:33]
	s_waitcnt lgkmcnt(9)
	v_alignbyte_b32 v228, v205, v204, v80
	v_alignbyte_b32 v229, v206, v205, v80
	v_alignbyte_b32 v230, v207, v206, v80
	v_alignbyte_b32 v231, v208, v207, v80
	ds_read2_b32 v[204:205], v157 offset0:32 offset1:33
	ds_read2_b32 v[206:207], v157 offset0:34 offset1:35
	ds_read_b32 v208, v157 offset:144
	ds_read_b128 v[236:239], v48 offset:128
	v_mfma_f32_16x16x32_bf16 v[34:37], v[228:231], v[240:243], v[34:37]
	s_waitcnt lgkmcnt(10)
	v_alignbyte_b32 v232, v211, v210, v80
	v_alignbyte_b32 v233, v212, v211, v80
	v_alignbyte_b32 v234, v213, v212, v80
	v_alignbyte_b32 v235, v214, v213, v80
	ds_read2_b32 v[210:211], v156 offset0:32 offset1:33
	ds_read2_b32 v[212:213], v156 offset0:34 offset1:35
	ds_read_b32 v214, v156 offset:144
	v_mfma_f32_16x16x32_bf16 v[38:41], v[232:235], v[240:243], v[38:41]
	s_waitcnt lgkmcnt(10)
	v_alignbyte_b32 v228, v217, v216, v80
	v_alignbyte_b32 v229, v218, v217, v80
	v_alignbyte_b32 v230, v219, v218, v80
	v_alignbyte_b32 v231, v220, v219, v80
	ds_read2_b32 v[216:217], v155 offset0:32 offset1:33
	ds_read2_b32 v[218:219], v155 offset0:34 offset1:35
	ds_read_b32 v220, v155 offset:144
	v_mfma_f32_16x16x32_bf16 v[26:29], v[228:231], v[240:243], v[26:29]
	s_waitcnt lgkmcnt(10)
	v_alignbyte_b32 v232, v223, v222, v80
	v_alignbyte_b32 v233, v224, v223, v80
	v_alignbyte_b32 v234, v225, v224, v80
	v_alignbyte_b32 v235, v226, v225, v80
	ds_read2_b32 v[222:223], v154 offset0:32 offset1:33
	ds_read2_b32 v[224:225], v154 offset0:34 offset1:35
	ds_read_b32 v226, v154 offset:144
	v_add_u32_e32 v48, 0x80, v48
	v_add_u32_e32 v154, 0x80, v154
	v_add_u32_e32 v155, 0x80, v155
	v_add_u32_e32 v156, 0x80, v156
	v_add_u32_e32 v157, 0x80, v157
	s_add_i32 s22, s22, 64
	s_cmpk_lt_i32 s22, 0x3c1
	v_mfma_f32_16x16x32_bf16 v[30:33], v[232:235], v[240:243], v[30:33]
	s_cbranch_scc1 .Lhl_conv_b
	s_waitcnt lgkmcnt(0)
	v_add_f32_e32 v42, v46, v47
	v_div_scale_f32 v43, s[22:23], v42, v42, 1.0
	v_rcp_f32_e32 v44, v43
	s_mov_b32 s22, 4
	s_mov_b64 s[90:91], 0
	s_mov_b64 s[92:93], -1
	v_fma_f32 v45, -v43, v44, 1.0
	v_fmac_f32_e32 v44, v45, v44
	v_div_scale_f32 v45, vcc, 1.0, v42, 1.0
	v_mul_f32_e32 v46, v45, v44
	v_fma_f32 v47, -v43, v46, v45
	v_fmac_f32_e32 v46, v47, v44
	v_fma_f32 v43, -v43, v46, v45
	v_div_fmas_f32 v43, v43, v44, v46
	ds_read2st64_b64 v[44:47], v59 offset0:1 offset1:2
	v_div_fixup_f32 v42, v43, v42, 1.0
	s_and_b64 vcc, exec, s[88:89]
	s_waitcnt lgkmcnt(0)
	v_and_b32_e32 v49, 0xffff0000, v44
	v_lshlrev_b32_e32 v48, 16, v44
	s_waitcnt vmcnt(0)
	v_pk_mul_f32 v[48:49], v[64:65], v[48:49] op_sel_hi:[0,1]
	v_pk_fma_f32 v[34:35], v[42:43], v[34:35], v[48:49] op_sel_hi:[0,1,1]
	v_and_b32_e32 v49, 0xffff0000, v45
	v_lshlrev_b32_e32 v48, 16, v45
	v_pk_mul_f32 v[44:45], v[64:65], v[48:49] op_sel_hi:[0,1]
	v_pk_fma_f32 v[36:37], v[42:43], v[36:37], v[44:45] op_sel_hi:[0,1,1]
	v_bfe_u32 v43, v37, 16, 1
	v_bfe_u32 v44, v36, 16, 1
	v_bfe_u32 v45, v35, 16, 1
	v_add3_u32 v45, v35, v45, s94
	v_add3_u32 v35, v36, v44, s94
	v_add3_u32 v36, v37, v43, s94
	v_perm_b32 v35, v36, v35, s95
	v_and_b32_e32 v37, 0xffff0000, v46
	v_lshlrev_b32_e32 v36, 16, v46
	v_pk_mul_f32 v[36:37], v[64:65], v[36:37] op_sel_hi:[0,1]
	v_pk_fma_f32 v[36:37], v[42:43], v[38:39], v[36:37] op_sel_hi:[0,1,1]
	v_and_b32_e32 v39, 0xffff0000, v47
	v_lshlrev_b32_e32 v38, 16, v47
	v_pk_mul_f32 v[38:39], v[64:65], v[38:39] op_sel_hi:[0,1]
	v_pk_fma_f32 v[38:39], v[42:43], v[40:41], v[38:39] op_sel_hi:[0,1,1]
	v_bfe_u32 v48, v34, 16, 1
	v_bfe_u32 v40, v39, 16, 1
	v_bfe_u32 v41, v38, 16, 1
	v_bfe_u32 v43, v37, 16, 1
	v_bfe_u32 v44, v36, 16, 1
	v_add3_u32 v34, v34, v48, s94
	v_add3_u32 v36, v36, v44, s94
	v_add3_u32 v43, v37, v43, s94
	v_add3_u32 v37, v38, v41, s94
	v_add3_u32 v38, v39, v40, s94
	v_perm_b32 v34, v45, v34, s95
	v_perm_b32 v37, v38, v37, s95
	v_perm_b32 v36, v43, v36, s95
	ds_write2st64_b64 v59, v[34:35], v[36:37] offset0:1 offset1:2
	ds_read2st64_b64 v[34:37], v59 offset0:3 offset1:4
	s_waitcnt lgkmcnt(0)
	v_and_b32_e32 v39, 0xffff0000, v34
	v_lshlrev_b32_e32 v38, 16, v34
	v_pk_mul_f32 v[38:39], v[64:65], v[38:39] op_sel_hi:[0,1]
	v_pk_fma_f32 v[26:27], v[42:43], v[26:27], v[38:39] op_sel_hi:[0,1,1]
	v_and_b32_e32 v39, 0xffff0000, v35
	v_lshlrev_b32_e32 v38, 16, v35
	v_pk_mul_f32 v[34:35], v[64:65], v[38:39] op_sel_hi:[0,1]
	v_pk_fma_f32 v[28:29], v[42:43], v[28:29], v[34:35] op_sel_hi:[0,1,1]
	v_bfe_u32 v34, v29, 16, 1
	v_bfe_u32 v35, v28, 16, 1
	v_bfe_u32 v38, v27, 16, 1
	v_add3_u32 v38, v27, v38, s94
	v_add3_u32 v27, v28, v35, s94
	v_add3_u32 v28, v29, v34, s94
	v_perm_b32 v27, v28, v27, s95
	v_and_b32_e32 v29, 0xffff0000, v36
	v_lshlrev_b32_e32 v28, 16, v36
	v_pk_mul_f32 v[28:29], v[64:65], v[28:29] op_sel_hi:[0,1]
	v_pk_fma_f32 v[28:29], v[42:43], v[30:31], v[28:29] op_sel_hi:[0,1,1]
	v_and_b32_e32 v31, 0xffff0000, v37
	v_lshlrev_b32_e32 v30, 16, v37
	v_pk_mul_f32 v[30:31], v[64:65], v[30:31] op_sel_hi:[0,1]
	v_pk_fma_f32 v[30:31], v[42:43], v[32:33], v[30:31] op_sel_hi:[0,1,1]
	v_bfe_u32 v39, v26, 16, 1
	v_bfe_u32 v32, v31, 16, 1
	v_bfe_u32 v33, v30, 16, 1
	v_bfe_u32 v34, v29, 16, 1
	v_bfe_u32 v35, v28, 16, 1
	v_add3_u32 v26, v26, v39, s94
	v_add3_u32 v28, v28, v35, s94
	v_add3_u32 v34, v29, v34, s94
	v_add3_u32 v29, v30, v33, s94
	v_add3_u32 v30, v31, v32, s94
	v_perm_b32 v26, v38, v26, s95
	v_perm_b32 v29, v30, v29, s95
	v_perm_b32 v28, v34, v28, s95
	ds_write2st64_b64 v59, v[26:27], v[28:29] offset0:3 offset1:4
	s_cbranch_vccz .LBB0_789
	v_cmp_eq_u32_e32 vcc, 0, v0
	s_and_saveexec_b64 s[42:43], vcc
	s_cbranch_execz .LBB0_838
	s_lshr_b32 s20, s20, 3
	s_and_b32 s20, s20, 4
	v_readlane_b32 s22, v251, 49
	s_add_u32 s20, s22, s20
	v_readlane_b32 s22, v251, 50
	s_addc_u32 s22, s22, 0
	s_lshl_b32 s21, s21, 5
	s_add_u32 s88, s20, s21
	s_addc_u32 s89, s22, 0
	s_mov_b32 s20, 0x400001
	s_branch .LBB0_807
